# rowpass row loop: last four butterfly steps of each wave-wide sum done with DPP moves (row_mirror, row_half_mirror, quad_perm) instead of ds_bpermute
# speedup vs baseline: 1.0022x; 1.0004x over previous
; DEV void unpack8(const u32x4 v, float (&f)[8]) { f[0] = bflo(v.x); f[1] = bfhi(v.x); f[2] = bflo(v.y); f[3] = bfhi(v.y); f[4] = bflo(v.z); f[5] = bfhi(v.z); f[6] = bflo(v.w); f[7] = bfhi(v.w); }
; DEV void phase_rowpass(const bf16_t* P, const float* conv_a, const float* lng, const float* lnb, bf16_t* OA, bf16_t* VN, const float* GLA, const float* GFA) {
;     ...
;     for (int rp = blockIdx.x * 8 + wave; rp < T_ / 2; rp += gridDim.x * 8) {
;         const int row = rp * 2;
;         const bf16_t* pr = P + (size_t)row * NP;
;         u32x4 vr[2][2];
; #pragma unroll
;         for (int r = 0; r < 2; ++r)
; #pragma unroll
;             for (int hlf = 0; hlf < 2; ++hlf) vr[r][hlf] = *(const u32x4*)(pr + (size_t)r * NP + COL_V + hlf * 512 + lane * 8);
; #pragma unroll
;         for (int r = 0; r < 2; ++r) {
;             float v[2][8]; float sm = 0.f;
; #pragma unroll
;             for (int hlf = 0; hlf < 2; ++hlf) { unpack8(vr[r][hlf], v[hlf]);
; #pragma unroll
;                 for (int j = 0; j < 8; ++j) sm += v[hlf][j]; }
;             const float mu = wave_sum(sm) * (1.f / 1024.f);
;             float q = 0.f;
; #pragma unroll
;             for (int hlf = 0; hlf < 2; ++hlf)
; #pragma unroll
;                 for (int j = 0; j < 8; ++j) { const float d = v[hlf][j] - mu; q += d * d; }
;             const float rstd = rsqrtf(wave_sum(q) * (1.f / 1024.f) + EPS_);
.LBB0_301:
	v_mov_b64_e32 v[38:39], v[88:89]
	v_mov_b64_e32 v[40:41], v[90:91]
	v_mov_b64_e32 v[42:43], v[92:93]
	v_mov_b64_e32 v[44:45], v[94:95]
	v_mov_b64_e32 v[78:79], v[96:97]
	v_mov_b64_e32 v[80:81], v[98:99]
	v_mov_b64_e32 v[82:83], v[100:101]
	v_mov_b64_e32 v[84:85], v[102:103]
	v_add_u32_e32 v46, s4, v46
	v_add_u32_e32 v113, s5, v36
	s_movk_i32 s6, 0x2000
	v_cmp_gt_i32_e32 vcc, s6, v46
	s_nop 1
	v_cndmask_b32_e32 v112, v36, v113, vcc
	v_mov_b64_e32 v[104:105], s[76:77]
	v_mad_i64_i32 v[104:105], s[6:7], v112, s59, v[104:105]
	v_lshl_add_u64 v[106:107], v[104:105], 0, v[0:1]
	s_mov_b64 s[6:7], 0x3000
	v_lshl_add_u64 v[104:105], v[106:107], 0, s[6:7]
	global_load_dwordx4 v[88:91], v[104:105], off offset:1024
	s_mov_b64 s[6:7], 0x3400
	v_lshl_add_u64 v[108:109], v[106:107], 0, s[6:7]
	global_load_dwordx4 v[92:95], v[108:109], off offset:1024
	s_mov_b64 s[6:7], 0x8000
	v_lshl_add_u64 v[110:111], v[106:107], 0, s[6:7]
	global_load_dwordx4 v[96:99], v[110:111], off offset:2560
	s_mov_b64 s[6:7], 0x8a00
	v_lshl_add_u64 v[104:105], v[106:107], 0, s[6:7]
	global_load_dwordx4 v[100:103], v[104:105], off offset:1024
	s_movk_i32 s6, 0x1fff
	v_lshlrev_b32_e32 v72, 16, v38
	v_and_b32_e32 v71, 0xffff0000, v38
	v_add_f32_e32 v37, 0, v72
	v_lshlrev_b32_e32 v70, 16, v39
	v_add_f32_e32 v37, v37, v71
	v_and_b32_e32 v69, 0xffff0000, v39
	v_add_f32_e32 v37, v37, v70
	v_lshlrev_b32_e32 v76, 16, v40
	v_add_f32_e32 v37, v37, v69
	v_and_b32_e32 v75, 0xffff0000, v40
	v_add_f32_e32 v37, v37, v76
	v_lshlrev_b32_e32 v74, 16, v41
	v_add_f32_e32 v37, v37, v75
	v_and_b32_e32 v73, 0xffff0000, v41
	v_add_f32_e32 v37, v37, v74
	v_lshlrev_b32_e32 v68, 16, v42
	v_add_f32_e32 v37, v37, v73
	v_and_b32_e32 v67, 0xffff0000, v42
	v_add_f32_e32 v37, v37, v68
	v_lshlrev_b32_e32 v66, 16, v43
	v_add_f32_e32 v37, v37, v67
	v_and_b32_e32 v65, 0xffff0000, v43
	v_add_f32_e32 v37, v37, v66
	v_lshlrev_b32_e32 v87, 16, v44
	v_add_f32_e32 v37, v37, v65
	v_and_b32_e32 v86, 0xffff0000, v44
	v_add_f32_e32 v37, v37, v87
	v_lshlrev_b32_e32 v43, 16, v45
	v_add_f32_e32 v37, v37, v86
	v_and_b32_e32 v42, 0xffff0000, v45
	v_add_f32_e32 v37, v37, v43
	v_add_f32_e32 v37, v37, v42
	ds_bpermute_b32 v45, v47, v37
	v_lshlrev_b32_e32 v63, 16, v78
	v_and_b32_e32 v61, 0xffff0000, v78
	v_add_f32_e32 v44, 0, v63
	v_lshlrev_b32_e32 v59, 16, v79
	v_add_f32_e32 v44, v44, v61
	v_and_b32_e32 v57, 0xffff0000, v79
	v_add_f32_e32 v44, v44, v59
	v_lshlrev_b32_e32 v64, 16, v80
	v_add_f32_e32 v44, v44, v57
	s_waitcnt lgkmcnt(0)
	v_add_f32_e32 v37, v37, v45
	v_and_b32_e32 v62, 0xffff0000, v80
	v_add_f32_e32 v44, v44, v64
	ds_bpermute_b32 v45, v48, v37
	v_lshlrev_b32_e32 v60, 16, v81
	v_add_f32_e32 v44, v44, v62
	v_and_b32_e32 v58, 0xffff0000, v81
	v_add_f32_e32 v44, v44, v60
	v_lshlrev_b32_e32 v56, 16, v82
	v_add_f32_e32 v44, v44, v58
	v_and_b32_e32 v55, 0xffff0000, v82
	v_add_f32_e32 v44, v44, v56
	v_lshlrev_b32_e32 v54, 16, v83
	v_add_f32_e32 v44, v44, v55
	s_waitcnt lgkmcnt(0)
	v_add_f32_e32 v37, v37, v45
	v_and_b32_e32 v53, 0xffff0000, v83
	v_add_f32_e32 v44, v44, v54
	s_nop 1
	v_mov_b32_dpp v45, v37 row_mirror row_mask:0xf bank_mask:0xf
	v_lshlrev_b32_e32 v41, 16, v84
	v_add_f32_e32 v44, v44, v53
	v_and_b32_e32 v40, 0xffff0000, v84
	v_add_f32_e32 v44, v44, v41
	v_lshlrev_b32_e32 v39, 16, v85
	v_add_f32_e32 v44, v44, v40
	v_and_b32_e32 v38, 0xffff0000, v85
	v_add_f32_e32 v44, v44, v39
	v_add_f32_e32 v44, v44, v38
	s_waitcnt lgkmcnt(0)
	v_add_f32_e32 v37, v37, v45
	ds_bpermute_b32 v77, v47, v44
	s_nop 1
	v_mov_b32_dpp v45, v37 row_half_mirror row_mask:0xf bank_mask:0xf
	s_waitcnt lgkmcnt(0)
	v_add_f32_e32 v44, v44, v77
	s_waitcnt lgkmcnt(0)
	v_add_f32_e32 v37, v37, v45
	ds_bpermute_b32 v77, v48, v44
	s_nop 1
	v_mov_b32_dpp v45, v37 quad_perm:[2,3,0,1] row_mask:0xf bank_mask:0xf
	s_waitcnt lgkmcnt(0)
	v_add_f32_e32 v44, v44, v77
	s_waitcnt lgkmcnt(0)
	v_add_f32_e32 v37, v37, v45
	s_nop 1
	v_mov_b32_dpp v77, v44 row_mirror row_mask:0xf bank_mask:0xf
	s_nop 1
	v_mov_b32_dpp v45, v37 quad_perm:[1,0,3,2] row_mask:0xf bank_mask:0xf
	s_waitcnt lgkmcnt(0)
	v_add_f32_e32 v44, v44, v77
	s_waitcnt lgkmcnt(0)
	v_add_f32_e32 v37, v37, v45
	s_nop 1
	v_mov_b32_dpp v77, v44 row_half_mirror row_mask:0xf bank_mask:0xf
	v_fmac_f32_e32 v71, 0xba800000, v37
	v_mul_f32_e32 v80, 0x3a800000, v37
	v_fmac_f32_e32 v72, 0xba800000, v37
	v_fmac_f32_e32 v70, 0xba800000, v37
	v_fmac_f32_e32 v69, 0xba800000, v37
	v_fmac_f32_e32 v76, 0xba800000, v37
	v_fmac_f32_e32 v75, 0xba800000, v37
	v_fmac_f32_e32 v74, 0xba800000, v37
	v_fmac_f32_e32 v73, 0xba800000, v37
	v_fmac_f32_e32 v68, 0xba800000, v37
	v_fmac_f32_e32 v67, 0xba800000, v37
	v_fmac_f32_e32 v66, 0xba800000, v37
	v_fmac_f32_e32 v65, 0xba800000, v37
	v_mul_f32_e32 v37, v71, v71
	v_fmac_f32_e32 v37, v72, v72
	v_fmac_f32_e32 v37, v70, v70
	v_fmac_f32_e32 v37, v69, v69
	s_waitcnt lgkmcnt(0)
	v_add_f32_e32 v44, v44, v77
	v_fmac_f32_e32 v37, v76, v76
	s_nop 1
	v_mov_b32_dpp v77, v44 quad_perm:[2,3,0,1] row_mask:0xf bank_mask:0xf
	v_fmac_f32_e32 v37, v75, v75
	v_fmac_f32_e32 v37, v74, v74
	v_fmac_f32_e32 v37, v73, v73
	v_fmac_f32_e32 v37, v68, v68
	v_fmac_f32_e32 v37, v67, v67
	s_waitcnt lgkmcnt(0)
	v_add_f32_e32 v77, v44, v77
	v_pk_add_f32 v[44:45], v[86:87], v[80:81] op_sel_hi:[1,0] neg_lo:[0,1] neg_hi:[0,1]
	v_fmac_f32_e32 v37, v66, v66
	v_pk_add_f32 v[42:43], v[42:43], v[80:81] op_sel_hi:[1,0] neg_lo:[0,1] neg_hi:[0,1]
	v_pk_mul_f32 v[80:81], v[44:45], v[44:45]
	v_fmac_f32_e32 v37, v65, v65
	v_add_f32_e32 v37, v81, v37
	v_pk_mul_f32 v[82:83], v[42:43], v[42:43]
	v_add_f32_e32 v37, v80, v37
	v_add_f32_e32 v37, v83, v37
	v_add_f32_e32 v79, v82, v37
	s_nop 1
	v_mov_b32_dpp v78, v77 quad_perm:[1,0,3,2] row_mask:0xf bank_mask:0xf
	ds_bpermute_b32 v80, v47, v79
	v_ashrrev_i32_e32 v37, 31, v36
	v_lshlrev_b64 v[82:83], 11, v[36:37]
	s_waitcnt lgkmcnt(0)
; DEV u32x4 pack8(const float (&f)[8]) { u32x4 w; w.x = cvt_pk_bf16(f[0], f[1]); w.y = cvt_pk_bf16(f[2], f[3]); w.z = cvt_pk_bf16(f[4], f[5]); w.w = cvt_pk_bf16(f[6], f[7]); return w; }
; DEV void phase_rowpass(const bf16_t* P, const float* conv_a, const float* lng, const float* lnb, bf16_t* OA, bf16_t* VN, const float* GLA, const float* GFA) {
;     ...
;             const float mu = wave_sum(sm) * (1.f / 1024.f);
;             float q = 0.f;
; #pragma unroll
;             for (int hlf = 0; hlf < 2; ++hlf)
; #pragma unroll
;                 for (int j = 0; j < 8; ++j) { const float d = v[hlf][j] - mu; q += d * d; }
;             const float rstd = rsqrtf(wave_sum(q) * (1.f / 1024.f) + EPS_);
; #pragma unroll
;             for (int hlf = 0; hlf < 2; ++hlf) { const int c = hlf * 512 + lane * 8; float o[8];
; #pragma unroll
;                 for (int j = 0; j < 4; ++j) { o[j] = (v[hlf][j] - mu) * rstd * g0[hlf][j] + b0[hlf][j]; o[4 + j] = (v[hlf][4 + j] - mu) * rstd * g1[hlf][j] + b1[hlf][j]; }
;                 *(u32x4*)(VN + (size_t)(row + r) * 1024 + c) = pack8(o); }
;         }
;     }
	v_add_f32_e32 v37, v77, v78
	s_waitcnt lgkmcnt(0)
	v_add_f32_e32 v77, v79, v80
	ds_bpermute_b32 v79, v48, v77
	v_mul_f32_e32 v78, 0x3a800000, v37
	v_fmac_f32_e32 v63, 0xba800000, v37
	v_fmac_f32_e32 v61, 0xba800000, v37
	v_fmac_f32_e32 v59, 0xba800000, v37
	s_waitcnt lgkmcnt(0)
	v_add_f32_e32 v77, v77, v79
	s_nop 1
	v_mov_b32_dpp v79, v77 row_mirror row_mask:0xf bank_mask:0xf
	v_fmac_f32_e32 v57, 0xba800000, v37
	v_fmac_f32_e32 v64, 0xba800000, v37
	v_fmac_f32_e32 v62, 0xba800000, v37
	v_fmac_f32_e32 v60, 0xba800000, v37
	s_waitcnt lgkmcnt(0)
	v_add_f32_e32 v77, v77, v79
	s_nop 1
	v_mov_b32_dpp v79, v77 row_half_mirror row_mask:0xf bank_mask:0xf
	v_fmac_f32_e32 v58, 0xba800000, v37
	v_fmac_f32_e32 v56, 0xba800000, v37
	v_fmac_f32_e32 v55, 0xba800000, v37
	v_fmac_f32_e32 v54, 0xba800000, v37
	v_fmac_f32_e32 v53, 0xba800000, v37
	s_waitcnt lgkmcnt(0)
	v_add_f32_e32 v37, v77, v79
	s_nop 1
	v_mov_b32_dpp v77, v37 quad_perm:[2,3,0,1] row_mask:0xf bank_mask:0xf
	v_mul_f32_e32 v79, v61, v61
	v_fmac_f32_e32 v79, v63, v63
	v_fmac_f32_e32 v79, v59, v59
	v_fmac_f32_e32 v79, v57, v57
	s_waitcnt lgkmcnt(0)
	v_add_f32_e32 v37, v37, v77
	s_nop 1
	v_mov_b32_dpp v77, v37 quad_perm:[1,0,3,2] row_mask:0xf bank_mask:0xf
	v_fmac_f32_e32 v79, v64, v64
	v_fmac_f32_e32 v79, v62, v62
	v_fmac_f32_e32 v79, v60, v60
	v_fmac_f32_e32 v79, v58, v58
	s_waitcnt lgkmcnt(0)
	v_add_f32_e32 v37, v37, v77
	v_fmamk_f32 v37, v37, 0x3a800000, v211
	v_mul_f32_e32 v77, 0x4b800000, v37
	v_cmp_gt_f32_e32 vcc, s33, v37
	v_fmac_f32_e32 v79, v56, v56
	v_fmac_f32_e32 v79, v55, v55
	v_cndmask_b32_e32 v37, v37, v77, vcc
	v_rsq_f32_e32 v37, v37
	v_fmac_f32_e32 v79, v54, v54
	v_fmac_f32_e32 v79, v53, v53
	v_pk_add_f32 v[40:41], v[40:41], v[78:79] op_sel_hi:[1,0] neg_lo:[0,1] neg_hi:[0,1]
	v_mul_f32_e32 v77, 0x45800000, v37
	v_cndmask_b32_e32 v37, v37, v77, vcc
	v_mul_f32_e32 v71, v71, v37
	v_mul_f32_e32 v70, v70, v37
	v_fma_f32 v77, v3, v71, v27
	v_fma_f32 v80, v4, v70, v28
	v_pk_mul_f32 v[70:71], v[40:41], v[40:41]
	v_mul_f32_e32 v69, v69, v37
	v_add_f32_e32 v71, v71, v79
	v_add_f32_e32 v79, v70, v71
	v_pk_add_f32 v[38:39], v[38:39], v[78:79] op_sel_hi:[1,0] neg_lo:[0,1] neg_hi:[0,1]
	v_mul_f32_e32 v72, v72, v37
	v_pk_mul_f32 v[70:71], v[38:39], v[38:39]
	v_mul_f32_e32 v76, v76, v37
	v_add_f32_e32 v71, v71, v79
	v_add_f32_e32 v78, v70, v71
	ds_bpermute_b32 v79, v47, v78
	v_fma_f32 v69, v5, v69, v29
	v_mul_f32_e32 v75, v75, v37
	v_fma_f32 v72, v2, v72, v26
	v_fma_f32 v76, v6, v76, v30
	v_cvt_pk_bf16_f32 v70, v72, v77
	v_cvt_pk_bf16_f32 v71, v80, v69
	s_waitcnt lgkmcnt(0)
	v_add_f32_e32 v69, v78, v79
	v_fma_f32 v75, v7, v75, v31
	v_cvt_pk_bf16_f32 v72, v76, v75
	ds_bpermute_b32 v76, v48, v69
	v_mul_f32_e32 v74, v74, v37
	v_mul_f32_e32 v73, v73, v37
	v_fma_f32 v74, v8, v74, v32
	v_fma_f32 v73, v9, v73, v33
	v_cvt_pk_bf16_f32 v73, v74, v73
	v_lshl_add_u64 v[74:75], v[34:35], 0, v[82:83]
	s_waitcnt lgkmcnt(0)
	v_add_f32_e32 v69, v69, v76
	global_store_dwordx4 v[74:75], v[70:73], off
	s_nop 1
	v_mov_b32_dpp v70, v69 row_mirror row_mask:0xf bank_mask:0xf
	v_mul_f32_e32 v43, v43, v37
	v_fma_f32 v71, v16, v43, v24
	v_mul_f32_e32 v43, v65, v37
	v_mul_f32_e32 v66, v66, v37
	s_waitcnt lgkmcnt(0)
	v_add_f32_e32 v69, v69, v70
	s_nop 1
	v_mov_b32_dpp v70, v69 row_half_mirror row_mask:0xf bank_mask:0xf
	v_mul_f32_e32 v68, v68, v37
	v_mul_f32_e32 v67, v67, v37
	v_fma_f32 v66, v12, v66, v20
	v_fma_f32 v43, v13, v43, v21
	s_waitcnt lgkmcnt(0)
	v_add_f32_e32 v69, v69, v70
	s_nop 1
	v_mov_b32_dpp v70, v69 quad_perm:[2,3,0,1] row_mask:0xf bank_mask:0xf
	v_fma_f32 v68, v10, v68, v18
	v_mul_f32_e32 v45, v45, v37
	v_fma_f32 v67, v11, v67, v19
	v_mul_f32_e32 v44, v44, v37
	s_waitcnt lgkmcnt(0)
	v_add_f32_e32 v65, v69, v70
	s_nop 1
	v_mov_b32_dpp v69, v65 quad_perm:[1,0,3,2] row_mask:0xf bank_mask:0xf
	v_mul_f32_e32 v37, v42, v37
	v_cvt_pk_bf16_f32 v42, v68, v67
	v_cvt_pk_bf16_f32 v43, v66, v43
	v_fma_f32 v45, v14, v45, v22
	s_waitcnt lgkmcnt(0)
	v_add_f32_e32 v65, v65, v69
	v_fmamk_f32 v65, v65, 0x3a800000, v211
	v_mul_f32_e32 v66, 0x4b800000, v65
	v_cmp_gt_f32_e32 vcc, s33, v65
	v_fma_f32 v44, v15, v44, v23
	v_fma_f32 v37, v17, v37, v25
	v_cndmask_b32_e32 v65, v65, v66, vcc
	v_rsq_f32_e32 v65, v65
	v_cvt_pk_bf16_f32 v44, v45, v44
	v_cvt_pk_bf16_f32 v45, v71, v37
	global_store_dwordx4 v[74:75], v[42:45], off offset:1024
	v_mul_f32_e32 v37, 0x45800000, v65
	v_cndmask_b32_e32 v37, v65, v37, vcc
	v_add_u32_e32 v42, 1, v36
	v_ashrrev_i32_e32 v43, 31, v42
	v_lshlrev_b64 v[66:67], 11, v[42:43]
	v_mul_f32_e32 v43, v64, v37
	v_mul_f32_e32 v42, v63, v37
	v_fma_f32 v44, v6, v43, v30
	v_mul_f32_e32 v43, v61, v37
	v_mul_f32_e32 v45, v62, v37
	v_mul_f32_e32 v59, v59, v37
	v_mul_f32_e32 v58, v58, v37
	v_fma_f32 v42, v2, v42, v26
	v_fma_f32 v43, v3, v43, v27
	v_fma_f32 v45, v7, v45, v31
	v_fma_f32 v59, v4, v59, v28
	v_mul_f32_e32 v60, v60, v37
	v_mul_f32_e32 v57, v57, v37
	v_fma_f32 v58, v9, v58, v33
	v_fma_f32 v60, v8, v60, v32
	v_fma_f32 v57, v5, v57, v29
	v_cvt_pk_bf16_f32 v42, v42, v43
	v_cvt_pk_bf16_f32 v43, v59, v57
	v_cvt_pk_bf16_f32 v44, v44, v45
	v_cvt_pk_bf16_f32 v45, v60, v58
	v_lshl_add_u64 v[58:59], v[34:35], 0, v[66:67]
	v_mul_f32_e32 v39, v39, v37
	global_store_dwordx4 v[58:59], v[42:45], off
	v_mul_f32_e32 v41, v41, v37
	v_mul_f32_e32 v40, v40, v37
	v_fma_f32 v45, v16, v39, v24
	v_mul_f32_e32 v39, v53, v37
	v_cmp_lt_i32_e32 vcc, s6, v46
	v_mul_f32_e32 v42, v56, v37
	v_fma_f32 v41, v14, v41, v22
	v_mul_f32_e32 v43, v55, v37
	v_fma_f32 v40, v15, v40, v23
	v_mul_f32_e32 v44, v54, v37
	v_fma_f32 v39, v13, v39, v21
	v_mul_f32_e32 v37, v38, v37
	s_or_b64 s[42:43], vcc, s[42:43]
	v_add_u32_e32 v36, s5, v36
	v_fma_f32 v42, v10, v42, v18
	v_fma_f32 v43, v11, v43, v19
	v_fma_f32 v44, v12, v44, v20
	v_fma_f32 v37, v17, v37, v25
	v_cvt_pk_bf16_f32 v38, v42, v43
	v_cvt_pk_bf16_f32 v39, v44, v39
	v_cvt_pk_bf16_f32 v40, v41, v40
	v_cvt_pk_bf16_f32 v41, v45, v37
	global_store_dwordx4 v[58:59], v[38:41], off offset:1024
	s_waitcnt vmcnt(4)
	s_andn2_b64 exec, exec, s[42:43]
	s_cbranch_execnz .LBB0_301
